# FoX step body hand-scheduled (K frags preloaded, exp/cvt interleaved with PV MFMA, next-tile bias before barrier) + GEMM tile order WGM 4 (P1) and 8 (P3)
# speedup vs baseline: 1.0090x; 1.0003x over previous
;     __host__ __device__ bool next(int i, Unit& u) const {
;         const long L = (long)i * G + c; if (L >= nwg) return false;
;         int wgid = (int)L; { const int q = nwg / NXCD, r = nwg % NXCD, xcd = wgid % NXCD, off = wgid / NXCD; wgid = (xcd < r ? xcd * (q + 1) : r * (q + 1) + (xcd - r) * q) + off; }
;         const int nig = WGM * nN, gid = wgid / nig, fm = gid * WGM, gsz = (nM - fm) < WGM ? (nM - fm) : WGM;
;         u.pm = fm + ((wgid % nig) % gsz); u.pn = (wgid % nig) / gsz; return true;
;     }
.LBB0_218:
	s_ashr_i32 s3, s3, 3
	s_add_i32 s3, s7, s3
	s_ashr_i32 s4, s3, 31
	s_lshr_b32 s4, s4, 24
	s_add_i32 s4, s3, s4
	s_ashr_i32 s5, s4, 6
	s_and_b32 s4, s4, 0xffffffc0
	s_sub_i32 s3, s3, s4
	s_sext_i32_i16 s4, s3
	s_bfe_u32 s4, s4, 0x4001b
	s_add_i32 s4, s3, s4
	s_sext_i32_i16 s6, s4
	s_and_b32 s4, s4, 0xfffc
	s_sub_i32 s3, s3, s4
	s_lshl_b32 s5, s5, 2
	s_sext_i32_i16 s3, s3
	s_add_i32 s28, s5, s3
	s_ashr_i32 s6, s6, 2

;     __host__ __device__ bool next(int i, Unit& u) const {
;         const long L = (long)i * G + c; if (L >= nwg) return false;
;         int wgid = (int)L; { const int q = nwg / NXCD, r = nwg % NXCD, xcd = wgid % NXCD, off = wgid / NXCD; wgid = (xcd < r ? xcd * (q + 1) : r * (q + 1) + (xcd - r) * q) + off; }
;         const int nig = WGM * nN, gid = wgid / nig, fm = gid * WGM, gsz = (nM - fm) < WGM ? (nM - fm) : WGM;
;         u.pm = fm + ((wgid % nig) % gsz); u.pn = (wgid % nig) / gsz; return true;
;     }
; template <class Epi, class Sched, bool ALIGN_EPI = false, bool SP2 = false>
; __device__ __forceinline__ void gemm_phase(PG8_LAS unsigned char* lds, const Gemm g, const Sched& S, const Epi& E, const int tid) {
;     ...
;         const bool has_next = S.next(ui + 1, nxt);
.LBB0_230:
	s_ashr_i32 s7, s7, 3
	s_add_i32 s7, s19, s7
	s_ashr_i32 s16, s7, 31
	s_lshr_b32 s16, s16, 24
	s_add_i32 s16, s7, s16
	s_ashr_i32 s17, s16, 6
	s_lshl_b32 s17, s17, 2
	s_sub_i32 s18, 0x100, s17
	s_min_i32 s18, s18, 4
	s_abs_i32 s19, s18
	v_cvt_f32_u32_e32 v0, s19
	s_sub_i32 s21, 0, s19
	s_and_b32 s16, s16, 0xffffffc0
	s_sub_i32 s7, s7, s16
	v_rcp_iflag_f32_e32 v0, v0
	s_abs_i32 s16, s7
	s_xor_b32 s20, s7, s18
	s_ashr_i32 s20, s20, 31
	v_mul_f32_e32 v0, 0x4f7ffffe, v0
	v_cvt_u32_f32_e32 v0, v0
	s_nop 0
	v_readfirstlane_b32 s22, v0
	s_mul_i32 s21, s21, s22
	s_mul_hi_u32 s21, s22, s21
	s_add_i32 s22, s22, s21
	s_mul_hi_u32 s21, s16, s22
	s_mul_i32 s22, s21, s19
	s_sub_i32 s16, s16, s22
	s_add_i32 s23, s21, 1
	s_sub_i32 s22, s16, s19
	s_cmp_ge_u32 s16, s19
	s_cselect_b32 s21, s23, s21
	s_cselect_b32 s16, s22, s16
	s_add_i32 s22, s21, 1
	s_cmp_ge_u32 s16, s19
	s_cselect_b32 s16, s22, s21
	s_xor_b32 s16, s16, s20
	s_sub_i32 s16, s16, s20
	s_mul_i32 s18, s16, s18
	s_sub_i32 s7, s7, s18
	s_add_i32 s18, s17, s7

; template <int MODE>
; __device__ __forceinline__ void step64(St& S, const bf16x8 (&qf)[4], int t, int qpos0, bool diag, bool first, float cq, float cfar, const LAS float* tab,
;                                        const LAS unsigned char* buf, unsigned vaddr, int r32, int hi) {
;     bf16x8 ka[4], kc[4];
; #pragma unroll
;     for (int d0 = 0; d0 < 4; ++d0) { const int o = r32 * 128 + (((d0 * 2 + hi) ^ ((r32 >> 1) & 7)) << 4); ka[d0] = *(const LAS bf16x8*)(buf + o); kc[d0] = *(const LAS bf16x8*)(buf + 4096 + o); }
;     f32x16 sa, sb;
;     if (MODE == 1) {
;         const float nm = cq - S.m;
; #pragma unroll
;         for (int g = 0; g < 4; ++g) { const f32x4 c0 = *(const LAS f32x4*)(tab + t * 64 + 8 * g + 4 * hi), c1 = *(const LAS f32x4*)(tab + t * 64 + 32 + 8 * g + 4 * hi);
; #pragma unroll
;             for (int e = 0; e < 4; ++e) { sa[4 * g + e] = nm - c0[e]; sb[4 * g + e] = nm - c1[e]; } }
;     } else {
;         if (qpos0 - (t * 64 + 31) >= 128) {
;             const float c = cfar - S.m;
; #pragma unroll
;             for (int r = 0; r < 16; ++r) sa[r] = c;
;         } else {
;             const int dd = qpos0 + r32 - t * 64 + 128;
; #pragma unroll
;             for (int r = 0; r < 16; ++r) { int idx = dd - crow(r, hi); idx = idx < 0 ? 0 : (idx > 256 ? 256 : idx); sa[r] = tab[idx] - S.m; }
;         }
;         if (qpos0 - (t * 64 + 63) >= 128) {
;             const float c = cfar - S.m;
; #pragma unroll
;             for (int r = 0; r < 16; ++r) sb[r] = c;
;         } else {
;             const int dd = qpos0 + r32 - t * 64 - 32 + 128;
; #pragma unroll
;             for (int r = 0; r < 16; ++r) { int idx = dd - crow(r, hi); idx = idx < 0 ? 0 : (idx > 256 ? 256 : idx); sb[r] = tab[idx] - S.m; }
;         }
;     }
; #pragma unroll
;     for (int d0 = 0; d0 < 4; ++d0) { sa = __builtin_amdgcn_mfma_f32_32x32x16_bf16(ka[d0], qf[d0], sa, 0, 0, 0); sb = __builtin_amdgcn_mfma_f32_32x32x16_bf16(kc[d0], qf[d0], sb, 0, 0, 0); }
;     s16x4 vlo[8], vhi[8];
;     ...
;     ATT_TR(vlo[0], 0);           ATT_TR(vhi[0], 1024);          ATT_TR(vlo[1], 2048);        ATT_TR(vhi[1], 3072);
;     ATT_TR(vlo[2], 512);         ATT_TR(vhi[2], 1536);          ATT_TR(vlo[3], 2560);        ATT_TR(vhi[3], 3584);
;     ATT_TR(vlo[4], 4096 + 0);    ATT_TR(vhi[4], 4096 + 1024);   ATT_TR(vlo[5], 4096 + 2048); ATT_TR(vhi[5], 4096 + 3072);
.LBB0_641:
	s_add_i32 s6, s11, 0
	s_add_i32 s5, s6, 0x6800
	s_add_i32 s4, s15, s1
	s_cmp_eq_u32 s4, 1
	v_add_u32_e32 v0, s6, v143
	v_add_u32_e32 v14, s6, v144
	v_add_u32_e32 v15, s6, v145
	v_add_u32_e32 v151, s6, v146
	ds_read_b128 v[186:189], v0 offset:18432
	ds_read_b128 v[194:197], v14 offset:18432
	ds_read_b128 v[202:205], v15 offset:18432
	ds_read_b128 v[210:213], v151 offset:18432
	ds_read_b128 v[190:193], v0 offset:22528
	ds_read_b128 v[198:201], v14 offset:22528
	ds_read_b128 v[206:209], v15 offset:22528
	ds_read_b128 v[214:217], v151 offset:22528
	v_add_u32_e32 v0, s5, v147
	s_cbranch_scc0 .Lm1_have_init
	ds_read_b128 v[112:115], v148
	ds_read_b128 v[104:107], v148 offset:32
	ds_read_b128 v[108:111], v148 offset:64
	ds_read_b128 v[100:103], v148 offset:96
	ds_read_b128 v[96:99], v148 offset:128
	ds_read_b128 v[6:9], v148 offset:160
	ds_read_b128 v[10:13], v148 offset:192
	ds_read_b128 v[2:5], v148 offset:224
	v_sub_f32_e32 v151, v142, v150
	s_waitcnt lgkmcnt(0)
	v_sub_f32_e32 v48, v151, v112
	v_sub_f32_e32 v49, v151, v113
	v_sub_f32_e32 v50, v151, v114
	v_sub_f32_e32 v51, v151, v115
	v_sub_f32_e32 v52, v151, v104
	v_sub_f32_e32 v53, v151, v105
	v_sub_f32_e32 v54, v151, v106
	v_sub_f32_e32 v55, v151, v107
	v_sub_f32_e32 v56, v151, v108
	v_sub_f32_e32 v57, v151, v109
	v_sub_f32_e32 v58, v151, v110
	v_sub_f32_e32 v59, v151, v111
	v_sub_f32_e32 v60, v151, v100
	v_sub_f32_e32 v61, v151, v101
	v_sub_f32_e32 v62, v151, v102
	v_sub_f32_e32 v63, v151, v103
	v_sub_f32_e32 v64, v151, v96
	v_sub_f32_e32 v65, v151, v97
	v_sub_f32_e32 v66, v151, v98
	v_sub_f32_e32 v67, v151, v99
	v_sub_f32_e32 v68, v151, v6
	v_sub_f32_e32 v69, v151, v7
	v_sub_f32_e32 v70, v151, v8
	v_sub_f32_e32 v71, v151, v9
	v_sub_f32_e32 v72, v151, v10
	v_sub_f32_e32 v73, v151, v11
	v_sub_f32_e32 v74, v151, v12
	v_sub_f32_e32 v75, v151, v13
	v_sub_f32_e32 v76, v151, v2
	v_sub_f32_e32 v77, v151, v3
	v_sub_f32_e32 v78, v151, v4
	v_sub_f32_e32 v79, v151, v5
	s_nop 1
.Lm1_have_init:
	s_waitcnt lgkmcnt(7)
	v_mfma_f32_32x32x16_bf16 v[48:63], v[186:189], v[80:83], v[48:63]
	s_waitcnt lgkmcnt(6)
	v_mfma_f32_32x32x16_bf16 v[48:63], v[194:197], v[84:87], v[48:63]
	s_waitcnt lgkmcnt(5)
	v_mfma_f32_32x32x16_bf16 v[48:63], v[202:205], v[88:91], v[48:63]
	s_waitcnt lgkmcnt(4)
	v_mfma_f32_32x32x16_bf16 v[48:63], v[210:213], v[92:95], v[48:63]
	s_waitcnt lgkmcnt(3)
	v_mfma_f32_32x32x16_bf16 v[64:79], v[190:193], v[80:83], v[64:79]
	ds_read_b64_tr_b16 v[112:113], v0
	ds_read_b64_tr_b16 v[114:115], v0 offset:1024
	ds_read_b64_tr_b16 v[104:105], v0 offset:2048
	ds_read_b64_tr_b16 v[106:107], v0 offset:3072
	s_waitcnt lgkmcnt(6)
	v_mfma_f32_32x32x16_bf16 v[64:79], v[198:201], v[84:87], v[64:79]
	ds_read_b64_tr_b16 v[108:109], v0 offset:512
	ds_read_b64_tr_b16 v[110:111], v0 offset:1536
	ds_read_b64_tr_b16 v[100:101], v0 offset:2560
	ds_read_b64_tr_b16 v[102:103], v0 offset:3584
	s_waitcnt lgkmcnt(9)
	v_mfma_f32_32x32x16_bf16 v[64:79], v[206:209], v[88:91], v[64:79]
	ds_read_b64_tr_b16 v[96:97], v0 offset:4096
	ds_read_b64_tr_b16 v[98:99], v0 offset:5120
	ds_read_b64_tr_b16 v[6:7], v0 offset:6144
	ds_read_b64_tr_b16 v[8:9], v0 offset:7168
	s_waitcnt lgkmcnt(12)
	v_mfma_f32_32x32x16_bf16 v[64:79], v[214:217], v[92:95], v[64:79]
	s_waitcnt lgkmcnt(11)
	ds_read_b64_tr_b16 v[10:11], v0 offset:4608
	ds_read_b64_tr_b16 v[12:13], v0 offset:5632
	ds_read_b64_tr_b16 v[2:3], v0 offset:6656
	ds_read_b64_tr_b16 v[4:5], v0 offset:7680
	s_cmp_lg_u32 s4, 1
	s_cbranch_scc1 .Lm1_nodiag
	s_nop 7
	s_nop 3
	v_cndmask_b32_e64 v0, v48, v140, s[34:35]
	s_nop 0
	v_cndmask_b32_e64 v64, v64, v140, s[36:37]
	v_cndmask_b32_e64 v49, v140, v49, s[38:39]
	v_cndmask_b32_e64 v48, v0, v48, s[38:39]
	v_cndmask_b32_e64 v65, v65, v140, s[40:41]
	v_cndmask_b32_e64 v50, v50, v140, s[42:43]
	v_cndmask_b32_e64 v66, v66, v140, s[44:45]
	v_cndmask_b32_e64 v51, v51, v140, s[46:47]
	v_cndmask_b32_e64 v67, v67, v140, s[48:49]
	v_cndmask_b32_e64 v52, v52, v140, s[50:51]
	v_cndmask_b32_e64 v68, v68, v140, s[52:53]
	v_cndmask_b32_e64 v53, v53, v140, s[54:55]
	v_cndmask_b32_e64 v69, v69, v140, s[56:57]
	v_cndmask_b32_e64 v54, v54, v140, s[58:59]
	v_cndmask_b32_e64 v70, v70, v140, s[60:61]
	v_cndmask_b32_e64 v55, v55, v140, s[62:63]
	v_cndmask_b32_e64 v71, v71, v140, s[64:65]
	v_cndmask_b32_e64 v56, v56, v140, s[66:67]
	v_cndmask_b32_e64 v72, v72, v140, s[68:69]
	v_cndmask_b32_e64 v57, v57, v140, s[70:71]
	v_cndmask_b32_e64 v73, v73, v140, s[72:73]
	v_cndmask_b32_e64 v58, v58, v140, s[74:75]
	v_cndmask_b32_e64 v74, v74, v140, s[76:77]
	v_cndmask_b32_e64 v59, v59, v140, s[78:79]
	v_cndmask_b32_e64 v75, v75, v140, s[80:81]
	v_cndmask_b32_e64 v60, v60, v140, s[82:83]
	v_cndmask_b32_e64 v76, v76, v140, s[84:85]
	v_cndmask_b32_e64 v61, v61, v140, s[86:87]
	v_cndmask_b32_e64 v77, v77, v140, s[88:89]
	v_cndmask_b32_e64 v62, v62, v140, s[90:91]
	v_cndmask_b32_e64 v78, v78, v140, s[92:93]
	v_cndmask_b32_e64 v63, v63, v140, s[94:95]
	v_cndmask_b32_e64 v79, v79, v140, s[96:97]
; #define LAS __attribute__((address_space(3)))
; __device__ __forceinline__ float max3f(float a, float b, float c) { float r; asm("v_max3_f32 %0, %1, %2, %3" : "=v"(r) : "v"(a), "v"(b), "v"(c)); return r; }
; template <int MODE>
; __device__ __forceinline__ void step64(St& S, const bf16x8 (&qf)[4], int t, int qpos0, bool diag, bool first, float cq, float cfar, const LAS float* tab,
;                                        const LAS unsigned char* buf, unsigned vaddr, int r32, int hi) {
;     ...
;         const float nm = cq - S.m;
; #pragma unroll
;         for (int g = 0; g < 4; ++g) { const f32x4 c0 = *(const LAS f32x4*)(tab + t * 64 + 8 * g + 4 * hi), c1 = *(const LAS f32x4*)(tab + t * 64 + 32 + 8 * g + 4 * hi);
; #pragma unroll
;             for (int e = 0; e < 4; ++e) { sa[4 * g + e] = nm - c0[e]; sb[4 * g + e] = nm - c1[e]; } }
;     ...
;     float r0 = max3f(sa[0], sa[1], sa[2]), r1 = max3f(sb[0], sb[1], sb[2]);
; #pragma unroll
;     for (int r = 3; r < 15; r += 2) { r0 = max3f(r0, sa[r], sa[r + 1]); r1 = max3f(r1, sb[r], sb[r + 1]); }
;     float rm = max3f(r0, r1, fmaxf(sa[15], sb[15]));
;     rm = xhalf_max(rm);
;     if (first || __any(rm > THR)) {
;         const float dl = first ? rm : fmaxf(rm, 0.f); S.m += dl;
;         const float f = first ? 1.0f : __builtin_amdgcn_exp2f(-dl); S.l *= f;
; #pragma unroll
;         for (int r = 0; r < 16; ++r) { sa[r] -= dl; sb[r] -= dl; S.o0[r] *= f; S.o1[r] *= f; }
;     }
.Lm1_nodiag:
	v_max3_f32 v0, v48, v49, v50
	v_max3_f32 v0, v0, v51, v52
	v_max3_f32 v0, v0, v53, v54
	v_max3_f32 v0, v0, v55, v56
	v_max3_f32 v0, v0, v57, v58
	v_max3_f32 v0, v0, v59, v60
	v_max3_f32 v0, v0, v61, v62
	s_nop 1
	v_max3_f32 v14, v64, v65, v66
	v_max3_f32 v14, v14, v67, v68
	v_max3_f32 v14, v14, v69, v70
	v_max3_f32 v14, v14, v71, v72
	v_max3_f32 v14, v14, v73, v74
	v_max3_f32 v14, v14, v75, v76
	v_max3_f32 v14, v14, v77, v78
	v_max_f32_e32 v15, v63, v79
	v_max3_f32 v0, v0, v14, v15
	s_nop 0
	v_mov_b32_e32 v14, v0
	s_nop 1
	v_permlane32_swap_b32_e32 v0, v14
	v_max_f32_e32 v14, v0, v14
	s_cmp_eq_u32 s4, 1
	s_cbranch_scc1 .Lm1_first
	s_mov_b32 s5, 0x41000000
	v_cmp_lt_f32_e32 vcc, s5, v14
	s_nop 3
	s_cbranch_vccz .Lm1_norescale
	v_max_f32_e32 v0, 0, v14
	v_exp_f32_e64 v14, -v0
	v_add_f32_e32 v150, v150, v0
	v_sub_f32_e32 v48, v48, v0
	v_sub_f32_e32 v49, v49, v0
	v_sub_f32_e32 v50, v50, v0
	v_sub_f32_e32 v51, v51, v0
	v_sub_f32_e32 v52, v52, v0
	v_sub_f32_e32 v53, v53, v0
	v_sub_f32_e32 v54, v54, v0
	v_sub_f32_e32 v55, v55, v0
	v_sub_f32_e32 v56, v56, v0
	v_sub_f32_e32 v57, v57, v0
	v_sub_f32_e32 v58, v58, v0
	v_sub_f32_e32 v59, v59, v0
	v_sub_f32_e32 v60, v60, v0
	v_sub_f32_e32 v61, v61, v0
	v_sub_f32_e32 v62, v62, v0
	v_sub_f32_e32 v63, v63, v0
	v_sub_f32_e32 v64, v64, v0
	v_sub_f32_e32 v65, v65, v0
	v_sub_f32_e32 v66, v66, v0
	v_sub_f32_e32 v67, v67, v0
	v_sub_f32_e32 v68, v68, v0
	v_sub_f32_e32 v69, v69, v0
	v_sub_f32_e32 v70, v70, v0
	v_sub_f32_e32 v71, v71, v0
	v_sub_f32_e32 v72, v72, v0
	v_sub_f32_e32 v73, v73, v0
	v_sub_f32_e32 v74, v74, v0
	v_sub_f32_e32 v75, v75, v0
	v_sub_f32_e32 v76, v76, v0
	v_sub_f32_e32 v77, v77, v0
	v_sub_f32_e32 v78, v78, v0
	v_sub_f32_e32 v79, v79, v0
	v_mul_f32_e32 v149, v149, v14
	v_mul_f32_e32 v16, v16, v14
	v_mul_f32_e32 v17, v17, v14
	v_mul_f32_e32 v18, v18, v14
	v_mul_f32_e32 v19, v19, v14
	v_mul_f32_e32 v20, v20, v14
	v_mul_f32_e32 v21, v21, v14
	v_mul_f32_e32 v22, v22, v14
	v_mul_f32_e32 v23, v23, v14
	v_mul_f32_e32 v24, v24, v14
	v_mul_f32_e32 v25, v25, v14
	v_mul_f32_e32 v26, v26, v14
	v_mul_f32_e32 v27, v27, v14
	v_mul_f32_e32 v28, v28, v14
	v_mul_f32_e32 v29, v29, v14
	v_mul_f32_e32 v30, v30, v14
	v_mul_f32_e32 v31, v31, v14
	v_mul_f32_e32 v32, v32, v14
	v_mul_f32_e32 v33, v33, v14
	v_mul_f32_e32 v34, v34, v14
	v_mul_f32_e32 v35, v35, v14
	v_mul_f32_e32 v36, v36, v14
	v_mul_f32_e32 v37, v37, v14
	v_mul_f32_e32 v38, v38, v14
	v_mul_f32_e32 v39, v39, v14
	v_mul_f32_e32 v40, v40, v14
	v_mul_f32_e32 v41, v41, v14
	v_mul_f32_e32 v42, v42, v14
	v_mul_f32_e32 v43, v43, v14
	v_mul_f32_e32 v44, v44, v14
	v_mul_f32_e32 v45, v45, v14
	v_mul_f32_e32 v46, v46, v14
	v_mul_f32_e32 v47, v47, v14
	s_branch .Lm1_norescale
.Lm1_first:
	v_add_f32_e32 v150, v150, v14
	v_sub_f32_e32 v48, v48, v14
	v_sub_f32_e32 v49, v49, v14
	v_sub_f32_e32 v50, v50, v14
	v_sub_f32_e32 v51, v51, v14
	v_sub_f32_e32 v52, v52, v14
	v_sub_f32_e32 v53, v53, v14
	v_sub_f32_e32 v54, v54, v14
	v_sub_f32_e32 v55, v55, v14
	v_sub_f32_e32 v56, v56, v14
	v_sub_f32_e32 v57, v57, v14
	v_sub_f32_e32 v58, v58, v14
	v_sub_f32_e32 v59, v59, v14
	v_sub_f32_e32 v60, v60, v14
	v_sub_f32_e32 v61, v61, v14
	v_sub_f32_e32 v62, v62, v14
	v_sub_f32_e32 v63, v63, v14
	v_sub_f32_e32 v64, v64, v14
	v_sub_f32_e32 v65, v65, v14
	v_sub_f32_e32 v66, v66, v14
	v_sub_f32_e32 v67, v67, v14
	v_sub_f32_e32 v68, v68, v14
	v_sub_f32_e32 v69, v69, v14
	v_sub_f32_e32 v70, v70, v14
	v_sub_f32_e32 v71, v71, v14
	v_sub_f32_e32 v72, v72, v14
	v_sub_f32_e32 v73, v73, v14
	v_sub_f32_e32 v74, v74, v14
	v_sub_f32_e32 v75, v75, v14
	v_sub_f32_e32 v76, v76, v14
	v_sub_f32_e32 v77, v77, v14
	v_sub_f32_e32 v78, v78, v14
	v_sub_f32_e32 v79, v79, v14
.Lm1_norescale:
	s_waitcnt lgkmcnt(0)
	s_cmp_eq_u32 s22, 0
	s_cbranch_scc1 .Lm1_pv
	v_add_u32_e32 v15, 0xffffff00, v148
	ds_read_b128 v[186:189], v15
	ds_read_b128 v[190:193], v15 offset:32
	ds_read_b128 v[194:197], v15 offset:64
	ds_read_b128 v[198:201], v15 offset:96
	ds_read_b128 v[202:205], v15 offset:128
	ds_read_b128 v[206:209], v15 offset:160
	ds_read_b128 v[210:213], v15 offset:192
	ds_read_b128 v[214:217], v15 offset:224
; #define LAS __attribute__((address_space(3)))
; template <int MODE>
; __device__ __forceinline__ void step64(St& S, const bf16x8 (&qf)[4], int t, int qpos0, bool diag, bool first, float cq, float cfar, const LAS float* tab,
;                                        const LAS unsigned char* buf, unsigned vaddr, int r32, int hi) {
;     ...
;         const float nm = cq - S.m;
; #pragma unroll
;         for (int g = 0; g < 4; ++g) { const f32x4 c0 = *(const LAS f32x4*)(tab + t * 64 + 8 * g + 4 * hi), c1 = *(const LAS f32x4*)(tab + t * 64 + 32 + 8 * g + 4 * hi);
; #pragma unroll
;             for (int e = 0; e < 4; ++e) { sa[4 * g + e] = nm - c0[e]; sb[4 * g + e] = nm - c1[e]; } }
;     ...
; #pragma unroll
;     for (int r = 0; r < 16; ++r) { sa[r] = __builtin_amdgcn_exp2f(sa[r]); sb[r] = __builtin_amdgcn_exp2f(sb[r]); }
;     asm volatile("s_waitcnt lgkmcnt(0)" ::: "memory");
;     __builtin_amdgcn_sched_barrier(0);
;     u32x4 pa0, pa1, pb0, pb1;
;     pa0.x = pk2(sa[0], sa[1]); pa0.y = pk2(sa[2], sa[3]); pa0.z = pk2(sa[4], sa[5]); pa0.w = pk2(sa[6], sa[7]);
;     pa1.x = pk2(sa[8], sa[9]); pa1.y = pk2(sa[10], sa[11]); pa1.z = pk2(sa[12], sa[13]); pa1.w = pk2(sa[14], sa[15]);
;     pb0.x = pk2(sb[0], sb[1]); pb0.y = pk2(sb[2], sb[3]); pb0.z = pk2(sb[4], sb[5]); pb0.w = pk2(sb[6], sb[7]);
;     pb1.x = pk2(sb[8], sb[9]); pb1.y = pk2(sb[10], sb[11]); pb1.z = pk2(sb[12], sb[13]); pb1.w = pk2(sb[14], sb[15]);
;     ...
;     S.o0 = __builtin_amdgcn_mfma_f32_32x32x16_bf16(ATT_VF(0), ATT_PF(pa0), S.o0, 0, 0, 0);
;     S.o1 = __builtin_amdgcn_mfma_f32_32x32x16_bf16(ATT_VF(2), ATT_PF(pa0), S.o1, 0, 0, 0);
;     S.o0 = __builtin_amdgcn_mfma_f32_32x32x16_bf16(ATT_VF(1), ATT_PF(pa1), S.o0, 0, 0, 0);
;     S.o1 = __builtin_amdgcn_mfma_f32_32x32x16_bf16(ATT_VF(3), ATT_PF(pa1), S.o1, 0, 0, 0);
;     S.o0 = __builtin_amdgcn_mfma_f32_32x32x16_bf16(ATT_VF(4), ATT_PF(pb0), S.o0, 0, 0, 0);
;     S.o1 = __builtin_amdgcn_mfma_f32_32x32x16_bf16(ATT_VF(6), ATT_PF(pb0), S.o1, 0, 0, 0);
;     S.o0 = __builtin_amdgcn_mfma_f32_32x32x16_bf16(ATT_VF(5), ATT_PF(pb1), S.o0, 0, 0, 0);
;     S.o1 = __builtin_amdgcn_mfma_f32_32x32x16_bf16(ATT_VF(7), ATT_PF(pb1), S.o1, 0, 0, 0);
;     ...
;     float l0 = 0.f, l1 = 0.f, l2 = 0.f, l3 = 0.f;
; #pragma unroll
;     for (int r = 0; r < 16; r += 2) { l0 += sa[r]; l1 += sa[r + 1]; l2 += sb[r]; l3 += sb[r + 1]; }
;     S.l += (l0 + l1) + (l2 + l3);
.Lm1_pv:
	v_exp_f32_e32 v48, v48
	v_exp_f32_e32 v49, v49
	v_exp_f32_e32 v50, v50
	v_exp_f32_e32 v51, v51
	v_exp_f32_e32 v52, v52
	v_exp_f32_e32 v53, v53
	v_exp_f32_e32 v54, v54
	v_exp_f32_e32 v55, v55
	v_cvt_pk_bf16_f32 v152, v48, v49
	v_cvt_pk_bf16_f32 v153, v50, v51
	v_cvt_pk_bf16_f32 v154, v52, v53
	v_cvt_pk_bf16_f32 v155, v54, v55
	v_exp_f32_e32 v56, v56
	v_exp_f32_e32 v57, v57
	v_mfma_f32_32x32x16_bf16 v[32:47], v[112:115], v[152:155], v[32:47]
	v_exp_f32_e32 v58, v58
	v_exp_f32_e32 v59, v59
	v_exp_f32_e32 v60, v60
	v_exp_f32_e32 v61, v61
	v_exp_f32_e32 v62, v62
	v_exp_f32_e32 v63, v63
	v_mfma_f32_32x32x16_bf16 v[16:31], v[108:111], v[152:155], v[16:31]
	v_cvt_pk_bf16_f32 v156, v56, v57
	v_cvt_pk_bf16_f32 v157, v58, v59
	v_cvt_pk_bf16_f32 v158, v60, v61
	v_cvt_pk_bf16_f32 v159, v62, v63
	v_add_f32_e32 v0, v48, v50
	v_add_f32_e32 v0, v0, v52
	v_add_f32_e32 v14, v49, v51
	v_add_f32_e32 v14, v14, v53
	v_mfma_f32_32x32x16_bf16 v[32:47], v[104:107], v[156:159], v[32:47]
	v_exp_f32_e32 v64, v64
	v_exp_f32_e32 v65, v65
	v_exp_f32_e32 v66, v66
	v_exp_f32_e32 v67, v67
	v_exp_f32_e32 v68, v68
	v_exp_f32_e32 v69, v69
	v_exp_f32_e32 v70, v70
	v_exp_f32_e32 v71, v71
	v_mfma_f32_32x32x16_bf16 v[16:31], v[100:103], v[156:159], v[16:31]
	v_cvt_pk_bf16_f32 v160, v64, v65
	v_cvt_pk_bf16_f32 v161, v66, v67
	v_cvt_pk_bf16_f32 v162, v68, v69
	v_cvt_pk_bf16_f32 v163, v70, v71
	v_add_f32_e32 v0, v0, v54
	v_add_f32_e32 v0, v0, v56
	v_add_f32_e32 v14, v14, v55
	v_add_f32_e32 v14, v14, v57
	v_mfma_f32_32x32x16_bf16 v[32:47], v[96:99], v[160:163], v[32:47]
	v_exp_f32_e32 v72, v72
	v_exp_f32_e32 v73, v73
	v_exp_f32_e32 v74, v74
	v_exp_f32_e32 v75, v75
	v_exp_f32_e32 v76, v76
	v_exp_f32_e32 v77, v77
	v_exp_f32_e32 v78, v78
	v_exp_f32_e32 v79, v79
	v_mfma_f32_32x32x16_bf16 v[16:31], v[10:13], v[160:163], v[16:31]
	v_cvt_pk_bf16_f32 v164, v72, v73
	v_cvt_pk_bf16_f32 v165, v74, v75
	v_cvt_pk_bf16_f32 v166, v76, v77
	v_cvt_pk_bf16_f32 v167, v78, v79
	v_add_f32_e32 v0, v0, v58
	v_add_f32_e32 v0, v0, v60
	v_add_f32_e32 v0, v0, v62
	v_add_f32_e32 v14, v14, v59
	v_add_f32_e32 v14, v14, v61
	v_add_f32_e32 v14, v14, v63
	v_mfma_f32_32x32x16_bf16 v[32:47], v[6:9], v[164:167], v[32:47]
	v_add_f32_e32 v15, v64, v66
	v_add_f32_e32 v15, v15, v68
	v_add_f32_e32 v15, v15, v70
	v_add_f32_e32 v15, v15, v72
	v_add_f32_e32 v151, v65, v67
	v_add_f32_e32 v151, v151, v69
	v_add_f32_e32 v151, v151, v71
	v_add_f32_e32 v151, v151, v73
	v_mfma_f32_32x32x16_bf16 v[16:31], v[2:5], v[164:167], v[16:31]
	v_add_f32_e32 v15, v15, v74
	v_add_f32_e32 v15, v15, v76
	v_add_f32_e32 v15, v15, v78
	v_add_f32_e32 v151, v151, v75
	v_add_f32_e32 v151, v151, v77
	v_add_f32_e32 v151, v151, v79
	v_add_f32_e32 v0, v0, v14
	v_add_f32_e32 v15, v15, v151
	v_add_f32_e32 v0, v0, v15
	v_add_f32_e32 v149, v149, v0
	s_cmp_eq_u32 s22, 0
	s_cbranch_scc1 .Lm1_end
	v_sub_f32_e32 v151, v142, v150
	s_waitcnt lgkmcnt(0)
	v_sub_f32_e32 v48, v151, v186
	v_sub_f32_e32 v49, v151, v187
	v_sub_f32_e32 v50, v151, v188
	v_sub_f32_e32 v51, v151, v189
	v_sub_f32_e32 v52, v151, v190
	v_sub_f32_e32 v53, v151, v191
	v_sub_f32_e32 v54, v151, v192
	v_sub_f32_e32 v55, v151, v193
	v_sub_f32_e32 v56, v151, v194
	v_sub_f32_e32 v57, v151, v195
	v_sub_f32_e32 v58, v151, v196
	v_sub_f32_e32 v59, v151, v197
	v_sub_f32_e32 v60, v151, v198
	v_sub_f32_e32 v61, v151, v199
	v_sub_f32_e32 v62, v151, v200
	v_sub_f32_e32 v63, v151, v201
	v_sub_f32_e32 v64, v151, v202
	v_sub_f32_e32 v65, v151, v203
	v_sub_f32_e32 v66, v151, v204
	v_sub_f32_e32 v67, v151, v205
	v_sub_f32_e32 v68, v151, v206
	v_sub_f32_e32 v69, v151, v207
	v_sub_f32_e32 v70, v151, v208
	v_sub_f32_e32 v71, v151, v209
	v_sub_f32_e32 v72, v151, v210
	v_sub_f32_e32 v73, v151, v211
	v_sub_f32_e32 v74, v151, v212
	v_sub_f32_e32 v75, v151, v213
	v_sub_f32_e32 v76, v151, v214
	v_sub_f32_e32 v77, v151, v215
	v_sub_f32_e32 v78, v151, v216
	v_sub_f32_e32 v79, v151, v217
.Lm1_end:
	s_mov_b64 s[0:1], -1
	s_and_b64 vcc, exec, s[24:25]
	s_cbranch_vccnz .LBB0_639

; #define LAS __attribute__((address_space(3)))
; template <int MODE> ...
;     ...
;     for (int s = T0; s < T1; ++s) {
;         const int t = SU_T(s);
;         const bool more = (s + 2 < T1);
;         if (more) { glds16(kg + (size_t)SU_T(s + 2) * 4096, kdst + s2); glds16(vg + (size_t)SU_T(s + 2) * 4096, vdst + s2); }
;         LAS unsigned char* buf = ring + s0;
;         if (t >= t_lo && t < t_hi)
;             step64<MODE>(S, qf, t, qpos0, t == t_hi - 1, REV ? (t == t_hi - 1) : (t == t_lo), cq, cfar, tab, buf, (unsigned)(unsigned long)(buf + 8192) + vl, r32, hi);
;         if (more) asm volatile("s_waitcnt vmcnt(2) lgkmcnt(0)\n\ts_barrier" ::: "memory");
;         else      asm volatile("s_waitcnt vmcnt(0) lgkmcnt(0)\n\ts_barrier" ::: "memory");
;         const int sn = s0; s0 = s1; s1 = s2; s2 = sn;
;     }
.LBB0_653:
	s_add_i32 s19, s19, 1
	v_lshl_add_u64 v[116:117], v[116:117], 0, s[26:27]
	v_lshl_add_u64 v[118:119], v[118:119], 0, s[26:27]
	s_cmp_lg_u32 s22, 0
	v_add_u32_e32 v148, 0xffffff00, v148
	s_cbranch_scc0 .LBB0_596
	s_mov_b32 s1, s22
	s_mov_b32 s0, s10
	s_mov_b32 s10, s12
	s_mov_b32 s12, s11
	s_branch .LBB0_636
.LBB0_656:
	s_branch .LBB0_633

; #define PG8_STAGE(bufoff, gbase, voff) do { _Pragma("unroll") for (int _i = 0; _i < 2; ++_i) \
;         __builtin_amdgcn_global_load_lds((const unsigned*)((const char*)(gbase) + (voff)[_i]), (PG8_LAS unsigned*)(lds + (bufoff) + ldsw + _i * 8192), 16, 0, 0); } while (0)
; #define PG8_WAIT_V(n) asm volatile("s_waitcnt vmcnt(" #n ")" ::: "memory")
; #define PG8_BAR __builtin_amdgcn_s_barrier()
;     __host__ __device__ bool next(int i, Unit& u) const {
;         const long L = (long)i * G + c; if (L >= nwg) return false;
;         int wgid = (int)L; { const int q = nwg / NXCD, r = nwg % NXCD, xcd = wgid % NXCD, off = wgid / NXCD; wgid = (xcd < r ? xcd * (q + 1) : r * (q + 1) + (xcd - r) * q) + off; }
;         const int nig = WGM * nN, gid = wgid / nig, fm = gid * WGM, gsz = (nM - fm) < WGM ? (nM - fm) : WGM;
;         u.pm = fm + ((wgid % nig) % gsz); u.pn = (wgid % nig) / gsz; return true;
;     }
; template <class Epi, class Sched, bool ALIGN_EPI = false, bool SP2 = false>
; __device__ __forceinline__ void gemm_phase(PG8_LAS unsigned char* lds, const Gemm g, const Sched& S, const Epi& E, const int tid) {
;     ...
;     const char* cA = (const char*)g.A + (size_t)cur.pm * tstep; const char* cB = (const char*)g.Bt + (size_t)cur.pn * tstep;
;     S.a_ready(cur);
;     if constexpr (SP2) {
;         PG8_STAGE(PG8_SB(0, 0), cB, voffB); PG8_STAGE(PG8_SB(0, 1), cB + hstep, voffB); PG8_STAGE(PG8_SA(0, 0), cA, voffA); PG8_STAGE(PG8_SA(0, 1), cA + hstep, voffA);
;         if (wr == 1) PG8_BAR;
;         PG8_WAIT_V(2); PG8_BAR;
;         PG8_STAGE(PG8_SB(1, 0), cB + kstep, voffB); PG8_STAGE(PG8_SA(1, 0), cA + kstep, voffA); PG8_STAGE(PG8_SB(1, 1), cB + hstep + kstep, voffB);
;         PG8_WAIT_V(6); PG8_BAR;
.LBB0_722:
	v_ashrrev_i32_e32 v1, 31, v20
	v_lshrrev_b32_e32 v1, 26, v1
	v_add_u32_e32 v1, v20, v1
	v_ashrrev_i32_e32 v9, 6, v1
	v_bfe_i32 v1, v20, 27, 1
	v_lshlrev_b32_e32 v0, 4, v20
	v_lshrrev_b32_e32 v1, 22, v1
	v_add_u32_e32 v1, v0, v1
	v_and_b32_e32 v1, 0xfffffc00, v1
	v_sub_u32_e32 v1, v0, v1
	v_lshrrev_b32_e32 v2, 4, v1
	v_bitop3_b32 v2, v2, v1, 32 bitop3:0x6c
	v_ashrrev_i32_e32 v1, 31, v1
	v_lshrrev_b32_e32 v1, 26, v1
	v_add_u32_e32 v1, v2, v1
	v_ashrrev_i32_e32 v10, 6, v1
	v_lshlrev_b32_e32 v3, 3, v9
	v_mul_i32_i24_e32 v4, 64, v10
	v_and_b32_e32 v3, -16, v3
	v_sub_u32_e32 v2, v2, v4
	v_mov_b32_e32 v4, 1
	v_add_u32_e32 v1, v10, v3
	v_lshlrev_b32_e32 v3, 5, v9
	v_ashrrev_i16_sdwa v2, v4, sext(v2) dst_sel:DWORD dst_unused:UNUSED_PAD src0_sel:DWORD src1_sel:BYTE_0
	v_and_b32_e32 v3, 32, v3
	v_bfe_i32 v11, v2, 0, 16
	v_and_b32_e32 v6, 3, v10
	s_mov_b32 s3, 0x1fffe0
	v_add_lshl_u32 v3, v3, v11, 1
	v_add_u32_e32 v0, 0x2000, v0
	v_lshlrev_b32_e32 v2, 1, v1
	v_lshrrev_b32_e32 v5, 2, v1
	v_and_or_b32 v6, v1, s3, v6
	v_lshl_add_u32 v128, v1, 11, v3
	v_ashrrev_i32_e32 v1, 31, v0
	s_add_i32 s0, s6, s0
	v_lshrrev_b32_e32 v1, 22, v1
	s_ashr_i32 s6, s0, 31
	v_add_u32_e32 v1, v0, v1
	s_lshr_b32 s6, s6, 26
	v_ashrrev_i32_e32 v12, 10, v1
	s_add_i32 s6, s0, s6
	v_mul_i32_i24_e32 v1, 0x400, v12
	s_ashr_i32 s7, s6, 5
	s_and_b32 s6, s6, 0xffe0
	v_sub_u32_e32 v0, v0, v1
	s_sub_i32 s6, s0, s6
	v_and_b32_e32 v2, 24, v2
	v_and_b32_e32 v5, 4, v5
	v_lshrrev_b32_e32 v1, 4, v0
	s_bfe_i32 s0, s6, 0x80000
	v_or3_b32 v2, v6, v5, v2
	v_bitop3_b32 v0, v1, v0, 32 bitop3:0x6c
	s_bfe_u32 s0, s0, 0x4000b
	v_lshl_add_u32 v130, v2, 11, v3
	v_ashrrev_i32_e32 v2, 31, v0
	s_add_i32 s9, s6, s0
	v_lshrrev_b32_e32 v2, 26, v2
	s_bfe_i32 s0, s9, 0x80000
	s_and_b32 s9, s9, 0xf8
	v_add_u32_e32 v2, v0, v2
	s_sub_i32 s6, s6, s9
	v_lshlrev_b32_e32 v1, 3, v12
	v_ashrrev_i32_e32 v13, 6, v2
	v_and_b32_e32 v2, 0xc0, v2
	s_lshl_b32 s7, s7, 3
	s_sext_i32_i16 s0, s0
	s_sext_i32_i8 s6, s6
	s_ashr_i32 s1, s10, 8
	v_and_b32_e32 v1, -16, v1
	v_sub_u32_e32 v0, v0, v2
	s_lshr_b32 s0, s0, 3
	s_add_i32 s12, s7, s6
	v_add_u32_e32 v1, v13, v1
	v_ashrrev_i16_sdwa v0, v4, sext(v0) dst_sel:DWORD dst_unused:UNUSED_PAD src0_sel:DWORD src1_sel:BYTE_0
	v_and_b32_e32 v4, 3, v13
	s_ashr_i32 s8, s10, 6
	s_ashr_i32 s13, s12, 31
	s_bfe_i64 s[14:15], s[0:1], 0x100000
	v_and_or_b32 v4, v1, s3, v4
	s_lshl_b32 s3, s8, 10
	s_lshl_b64 s[6:7], s[12:13], 19
	s_lshl_b64 s[14:15], s[14:15], 19
	v_readlane_b32 s16, v241, 8
	v_readlane_b32 s17, v241, 9
	s_add_u32 s24, s16, s14
	v_lshlrev_b32_e32 v3, 5, v12
	v_bfe_i32 v14, v0, 0, 16
	v_lshlrev_b32_e32 v0, 1, v1
	v_lshrrev_b32_e32 v2, 2, v1
	s_addc_u32 s25, s17, s15
	s_add_i32 s13, s3, 0
	v_and_b32_e32 v3, 32, v3
	v_and_b32_e32 v0, 24, v0
	v_and_b32_e32 v2, 4, v2
	s_add_i32 m0, s13, 0x10000
	v_or3_b32 v0, v4, v2, v0
	v_add_lshl_u32 v2, v3, v14, 1
	global_load_lds_dwordx4 v130, s[24:25]
	s_add_i32 m0, s13, 0x12000
	v_lshl_add_u32 v134, v0, 11, v2
	s_add_u32 s14, s24, 0x40000
	global_load_lds_dwordx4 v134, s[24:25]
	s_addc_u32 s15, s25, 0
	s_add_i32 m0, s13, 0x14000
	v_lshl_add_u32 v132, v1, 11, v2
	global_load_lds_dwordx4 v130, s[14:15]
	s_add_i32 m0, s13, 0x16000
	s_add_u32 s22, s72, s6
	s_addc_u32 s23, s73, s7
	s_add_i32 s28, s13, 0x2000
	global_load_lds_dwordx4 v134, s[14:15]
	s_mov_b32 m0, s13
	s_add_u32 s6, s22, 0x40000
	global_load_lds_dwordx4 v128, s[22:23]
	s_mov_b32 m0, s28
	s_addc_u32 s7, s23, 0
	s_add_i32 s29, s13, 0x4000
	global_load_lds_dwordx4 v132, s[22:23]
	s_mov_b32 m0, s29
	s_add_i32 s30, s13, 0x6000
	global_load_lds_dwordx4 v128, s[6:7]
	s_mov_b32 m0, s30
	v_mov_b32_e32 v137, 0
	global_load_lds_dwordx4 v132, s[6:7]
	v_mov_b32_e32 v131, v137
	v_mov_b32_e32 v135, v137
	v_mov_b32_e32 v129, v137
	v_mov_b32_e32 v133, v137
	s_cmp_eq_u32 s1, 1
	s_mov_b32 s31, 0
	v_lshl_add_u64 v[6:7], s[24:25], 0, v[130:131]
	v_lshl_add_u64 v[4:5], s[24:25], 0, v[134:135]
	v_lshl_add_u64 v[0:1], s[22:23], 0, v[128:129]
	s_cselect_b64 s[6:7], -1, 0
	s_cmp_lg_u32 s1, 1
	v_lshl_add_u64 v[2:3], s[22:23], 0, v[132:133]
	s_cbranch_scc1 .LBB0_724
	s_barrier

;     __host__ __device__ bool next(int i, Unit& u) const {
;         const long L = (long)i * G + c; if (L >= nwg) return false;
;         int wgid = (int)L; { const int q = nwg / NXCD, r = nwg % NXCD, xcd = wgid % NXCD, off = wgid / NXCD; wgid = (xcd < r ? xcd * (q + 1) : r * (q + 1) + (xcd - r) * q) + off; }
;         const int nig = WGM * nN, gid = wgid / nig, fm = gid * WGM, gsz = (nM - fm) < WGM ? (nM - fm) : WGM;
;         u.pm = fm + ((wgid % nig) % gsz); u.pn = (wgid % nig) / gsz; return true;
;     }
; template <class Epi, class Sched, bool ALIGN_EPI = false, bool SP2 = false>
; __device__ __forceinline__ void gemm_phase(PG8_LAS unsigned char* lds, const Gemm g, const Sched& S, const Epi& E, const int tid) {
;     ...
;         const bool has_next = S.next(ui + 1, nxt);
.LBB0_732:
	s_ashr_i32 s14, s16, 3
	s_add_i32 s14, s18, s14
	s_ashr_i32 s15, s14, 31
	s_lshr_b32 s15, s15, 26
	s_add_i32 s15, s14, s15
	s_ashr_i32 s16, s15, 5
	s_lshl_b32 s16, s16, 3
	s_sub_i32 s17, 0x100, s16
	s_min_i32 s17, s17, 8
	s_abs_i32 s18, s17
	v_cvt_f32_u32_e32 v0, s18
	s_sub_i32 s20, 0, s18
	s_andn2_b32 s15, s15, 31
	s_sub_i32 s15, s14, s15
	v_rcp_iflag_f32_e32 v0, v0
	s_abs_i32 s14, s15
	s_xor_b32 s19, s15, s17
	s_ashr_i32 s19, s19, 31
	v_mul_f32_e32 v0, 0x4f7ffffe, v0
	v_cvt_u32_f32_e32 v0, v0
	s_nop 0
	v_readfirstlane_b32 s21, v0
	s_mul_i32 s20, s20, s21
	s_mul_hi_u32 s20, s21, s20
	s_add_i32 s21, s21, s20
	s_mul_hi_u32 s20, s14, s21
	s_mul_i32 s21, s20, s18
	s_sub_i32 s14, s14, s21
	s_add_i32 s26, s20, 1
	s_sub_i32 s21, s14, s18
	s_cmp_ge_u32 s14, s18
	s_cselect_b32 s20, s26, s20
	s_cselect_b32 s14, s21, s14
	s_add_i32 s21, s20, 1
	s_cmp_ge_u32 s14, s18
	s_cselect_b32 s14, s21, s20
	s_xor_b32 s14, s14, s19
	s_sub_i32 s14, s14, s19
	s_mul_i32 s17, s14, s17
	s_sub_i32 s15, s15, s17
	s_add_i32 s16, s16, s15
